# GEMM k-step: vmcnt wait and first LDS stores of each half moved behind MFMA group 0 (stores 3/3/2)
# speedup vs baseline: 1.0078x; 1.0078x over previous
.LBB0_886:
	v_add_u32_e32 v153, v148, v143
	s_waitcnt lgkmcnt(0)
	v_mfma_f32_32x32x16_bf16 v[16:31], v[162:165], v[158:161], v[16:31]
	s_cmp_gt_u32 s39, 12
	v_mfma_f32_32x32x16_bf16 v[48:63], v[154:157], v[158:161], v[48:63]
	v_mfma_f32_32x32x16_bf16 v[32:47], v[154:157], v[166:169], v[32:47]
	ds_read_b128 v[156:159], v153
	v_add_u32_e32 v154, v148, v145
	v_add_u32_e32 v155, v149, v143
	v_mfma_f32_32x32x16_bf16 v[0:15], v[162:165], v[166:169], v[0:15]
	ds_read_b128 v[160:163], v154 offset:16384
	ds_read_b128 v[164:167], v153 offset:4096
	ds_read_b128 v[168:171], v154 offset:20480
	s_mov_b64 vcc, s[6:7]
	s_cbranch_vccnz .Lg1w_w0
	s_waitcnt vmcnt(8)
	s_branch .Lg1w_w1

.Lg1w_w1:
	ds_write_b128 v141, v[68:71] offset:32768
	ds_write_b128 v141, v[76:79] offset:49152
	ds_write_b128 v141, v[84:87] offset:36864
	s_waitcnt lgkmcnt(3)
	v_mfma_f32_32x32x16_bf16 v[48:63], v[156:159], v[160:163], v[48:63]
	v_mfma_f32_32x32x16_bf16 v[32:47], v[156:159], v[168:171], v[32:47]
	v_add_u32_e32 v156, v149, v145
	v_add_u32_e32 v157, v150, v143
	v_mfma_f32_32x32x16_bf16 v[16:31], v[164:167], v[160:163], v[16:31]
	ds_read_b128 v[158:161], v155
	v_mfma_f32_32x32x16_bf16 v[0:15], v[164:167], v[168:171], v[0:15]
	ds_read_b128 v[162:165], v156 offset:16384
	ds_read_b128 v[166:169], v155 offset:4096
	ds_read_b128 v[170:173], v156 offset:20480
	ds_write_b128 v141, v[92:95] offset:53248
	ds_write_b128 v141, v[100:103] offset:40960
	ds_write_b128 v141, v[108:111] offset:57344
	s_waitcnt lgkmcnt(3)
	v_mfma_f32_32x32x16_bf16 v[48:63], v[158:161], v[162:165], v[48:63]
	v_mfma_f32_32x32x16_bf16 v[32:47], v[158:161], v[170:173], v[32:47]
	v_add_u32_e32 v158, v150, v145
	v_mfma_f32_32x32x16_bf16 v[16:31], v[166:169], v[162:165], v[16:31]
	ds_read_b128 v[160:163], v157
	v_mfma_f32_32x32x16_bf16 v[0:15], v[166:169], v[170:173], v[0:15]
	ds_read_b128 v[164:167], v158 offset:16384
	ds_read_b128 v[168:171], v157 offset:4096
	ds_read_b128 v[172:175], v158 offset:20480
	ds_write_b128 v141, v[116:119] offset:45056
	ds_write_b128 v141, v[124:127] offset:61440
	s_waitcnt lgkmcnt(2)
	v_mfma_f32_32x32x16_bf16 v[48:63], v[160:163], v[164:167], v[48:63]
	v_mfma_f32_32x32x16_bf16 v[32:47], v[160:163], v[172:175], v[32:47]
	v_mfma_f32_32x32x16_bf16 v[16:31], v[168:171], v[164:167], v[16:31]
	v_mfma_f32_32x32x16_bf16 v[0:15], v[168:171], v[172:175], v[0:15]
	s_waitcnt lgkmcnt(0)
	s_barrier
	ds_read_b128 v[160:163], v152 offset:49152
	ds_read_b128 v[164:167], v151 offset:36864
	ds_read_b128 v[168:171], v152 offset:53248
	s_cbranch_scc1 .LBB0_888
	v_add_co_u32_e32 v84, vcc, 0x10000, v136
	global_load_dwordx4 v[68:71], v[136:137], off offset:384
	global_load_dwordx4 v[76:79], v[134:135], off offset:384
	v_addc_co_u32_e32 v85, vcc, 0, v137, vcc
	v_add_co_u32_e32 v92, vcc, 0x10000, v134
	global_load_dwordx4 v[84:87], v[84:85], off offset:384
	s_nop 0
	v_addc_co_u32_e32 v93, vcc, 0, v135, vcc
	v_add_co_u32_e32 v100, vcc, 0x20000, v136
	global_load_dwordx4 v[92:95], v[92:93], off offset:384
	s_nop 0
	v_addc_co_u32_e32 v101, vcc, 0, v137, vcc
	v_add_co_u32_e32 v108, vcc, 0x20000, v134
	global_load_dwordx4 v[100:103], v[100:101], off offset:384
	s_nop 0
	v_addc_co_u32_e32 v109, vcc, 0, v135, vcc
	v_add_co_u32_e32 v116, vcc, 0x30000, v136
	global_load_dwordx4 v[108:111], v[108:109], off offset:384
	s_nop 0
	v_addc_co_u32_e32 v117, vcc, 0, v137, vcc
	v_add_co_u32_e32 v124, vcc, 0x30000, v134
	global_load_dwordx4 v[116:119], v[116:117], off offset:384
	s_nop 0
	v_addc_co_u32_e32 v125, vcc, 0, v135, vcc
	global_load_dwordx4 v[124:127], v[124:125], off offset:384
.LBB0_888:
	ds_read_b128 v[134:137], v151 offset:32768
	s_andn2_b64 vcc, exec, s[8:9]
	s_waitcnt lgkmcnt(0)
	v_mfma_f32_32x32x16_bf16 v[48:63], v[134:137], v[160:163], v[48:63]
	v_mfma_f32_32x32x16_bf16 v[32:47], v[134:137], v[168:171], v[32:47]
	ds_read_b128 v[134:137], v153 offset:32768
	v_mfma_f32_32x32x16_bf16 v[16:31], v[164:167], v[160:163], v[16:31]
	ds_read_b128 v[160:163], v154 offset:49152
	v_mfma_f32_32x32x16_bf16 v[0:15], v[164:167], v[168:171], v[0:15]
	ds_read_b128 v[164:167], v153 offset:36864
	ds_read_b128 v[168:171], v154 offset:53248
	s_waitcnt vmcnt(8)
	ds_write_b128 v141, v[64:67]
	ds_write_b128 v141, v[72:75] offset:16384
	ds_write_b128 v141, v[80:83] offset:4096
	s_waitcnt lgkmcnt(3)
	v_mfma_f32_32x32x16_bf16 v[48:63], v[134:137], v[160:163], v[48:63]
	v_mfma_f32_32x32x16_bf16 v[32:47], v[134:137], v[168:171], v[32:47]
	ds_read_b128 v[134:137], v155 offset:32768
	v_mfma_f32_32x32x16_bf16 v[16:31], v[164:167], v[160:163], v[16:31]
	ds_read_b128 v[160:163], v156 offset:49152
	ds_read_b128 v[152:155], v155 offset:36864
	v_mfma_f32_32x32x16_bf16 v[0:15], v[164:167], v[168:171], v[0:15]
	ds_read_b128 v[164:167], v156 offset:53248
	ds_write_b128 v141, v[88:91] offset:20480
	ds_write_b128 v141, v[96:99] offset:8192
	ds_write_b128 v141, v[104:107] offset:24576
	s_waitcnt lgkmcnt(3)
	v_mfma_f32_32x32x16_bf16 v[48:63], v[134:137], v[160:163], v[48:63]
	v_mfma_f32_32x32x16_bf16 v[32:47], v[134:137], v[164:167], v[32:47]
	ds_read_b128 v[134:137], v157 offset:32768
	v_mfma_f32_32x32x16_bf16 v[16:31], v[152:155], v[160:163], v[16:31]
	v_mfma_f32_32x32x16_bf16 v[0:15], v[152:155], v[164:167], v[0:15]
	ds_read_b128 v[152:155], v158 offset:49152
	ds_read_b128 v[160:163], v157 offset:36864
	ds_read_b128 v[156:159], v158 offset:53248
	ds_write_b128 v141, v[112:115] offset:12288
	ds_write_b128 v141, v[120:123] offset:28672
	s_waitcnt lgkmcnt(2)
	v_mfma_f32_32x32x16_bf16 v[48:63], v[134:137], v[152:155], v[48:63]
	v_mfma_f32_32x32x16_bf16 v[32:47], v[134:137], v[156:159], v[32:47]
	v_mfma_f32_32x32x16_bf16 v[16:31], v[160:163], v[152:155], v[16:31]
	v_mfma_f32_32x32x16_bf16 v[0:15], v[160:163], v[156:159], v[0:15]
	s_branch .LBB0_883

.LBB0_1010:
	v_add_u32_e32 v157, v143, v139
	s_waitcnt lgkmcnt(0)
	v_mfma_f32_32x32x16_bf16 v[0:15], v[226:229], v[222:225], v[0:15]
	v_add_u32_e32 v159, v143, v141
	v_add_u32_e32 v161, v149, v139
	v_add_u32_e32 v163, v149, v141
	v_add_u32_e32 v165, v151, v139
	v_add_u32_e32 v167, v151, v141
	s_cmp_gt_u32 s68, 12
	v_mfma_f32_32x32x16_bf16 v[32:47], v[218:221], v[222:225], v[32:47]
	v_mfma_f32_32x32x16_bf16 v[48:63], v[218:221], v[230:233], v[48:63]
	ds_read_b128 v[218:221], v157
	v_mfma_f32_32x32x16_bf16 v[16:31], v[226:229], v[230:233], v[16:31]
	ds_read_b128 v[222:225], v159 offset:16384
	ds_read_b128 v[226:229], v157 offset:4096
	ds_read_b128 v[230:233], v159 offset:20480
	s_mov_b64 vcc, s[0:1]
	s_cbranch_vccnz .Lkqw_w0
	s_waitcnt vmcnt(8)
	s_branch .Lkqw_w1

.Lkqw_w1:
	ds_write_b128 v135, v[68:71] offset:32768
	ds_write_b128 v135, v[76:79] offset:49152
	ds_write_b128 v135, v[84:87] offset:36864
	s_waitcnt lgkmcnt(3)
	v_mfma_f32_32x32x16_bf16 v[32:47], v[218:221], v[222:225], v[32:47]
	v_mfma_f32_32x32x16_bf16 v[48:63], v[218:221], v[230:233], v[48:63]
	ds_read_b128 v[218:221], v161
	v_mfma_f32_32x32x16_bf16 v[0:15], v[226:229], v[222:225], v[0:15]
	v_mfma_f32_32x32x16_bf16 v[16:31], v[226:229], v[230:233], v[16:31]
	ds_read_b128 v[222:225], v163 offset:16384
	ds_read_b128 v[226:229], v161 offset:4096
	ds_read_b128 v[230:233], v163 offset:20480
	ds_write_b128 v135, v[92:95] offset:53248
	ds_write_b128 v135, v[100:103] offset:40960
	ds_write_b128 v135, v[108:111] offset:57344
	s_waitcnt lgkmcnt(3)
	v_mfma_f32_32x32x16_bf16 v[32:47], v[218:221], v[222:225], v[32:47]
	v_mfma_f32_32x32x16_bf16 v[48:63], v[218:221], v[230:233], v[48:63]
	ds_read_b128 v[218:221], v165
	v_mfma_f32_32x32x16_bf16 v[0:15], v[226:229], v[222:225], v[0:15]
	v_mfma_f32_32x32x16_bf16 v[16:31], v[226:229], v[230:233], v[16:31]
	ds_read_b128 v[222:225], v167 offset:16384
	ds_read_b128 v[226:229], v165 offset:4096
	ds_read_b128 v[230:233], v167 offset:20480
	ds_write_b128 v135, v[116:119] offset:45056
	ds_write_b128 v135, v[124:127] offset:61440
	s_waitcnt lgkmcnt(2)
	v_mfma_f32_32x32x16_bf16 v[32:47], v[218:221], v[222:225], v[32:47]
	v_mfma_f32_32x32x16_bf16 v[48:63], v[218:221], v[230:233], v[48:63]
	v_mfma_f32_32x32x16_bf16 v[0:15], v[226:229], v[222:225], v[0:15]
	v_mfma_f32_32x32x16_bf16 v[16:31], v[226:229], v[230:233], v[16:31]
	s_waitcnt lgkmcnt(0)
	s_barrier
	ds_read_b128 v[218:221], v155 offset:49152
	ds_read_b128 v[222:225], v153 offset:36864
	ds_read_b128 v[226:229], v155 offset:53248
	s_cbranch_scc1 .LBB0_1012
	v_add_co_u32_e32 v84, vcc, 0x10000, v194
	global_load_dwordx4 v[68:71], v[194:195], off offset:384
	global_load_dwordx4 v[76:79], v[192:193], off offset:384
	v_addc_co_u32_e32 v85, vcc, 0, v195, vcc
	v_add_co_u32_e32 v92, vcc, 0x10000, v192
	global_load_dwordx4 v[84:87], v[84:85], off offset:384
	s_nop 0
	v_addc_co_u32_e32 v93, vcc, 0, v193, vcc
	v_add_co_u32_e32 v100, vcc, 0x20000, v194
	global_load_dwordx4 v[92:95], v[92:93], off offset:384
	s_nop 0
	v_addc_co_u32_e32 v101, vcc, 0, v195, vcc
	v_add_co_u32_e32 v108, vcc, 0x20000, v192
	global_load_dwordx4 v[100:103], v[100:101], off offset:384
	s_nop 0
	v_addc_co_u32_e32 v109, vcc, 0, v193, vcc
	v_add_co_u32_e32 v116, vcc, 0x30000, v194
	global_load_dwordx4 v[108:111], v[108:109], off offset:384
	s_nop 0
	v_addc_co_u32_e32 v117, vcc, 0, v195, vcc
	v_add_co_u32_e32 v124, vcc, 0x30000, v192
	global_load_dwordx4 v[116:119], v[116:117], off offset:384
	s_nop 0
	v_addc_co_u32_e32 v125, vcc, 0, v193, vcc
	global_load_dwordx4 v[124:127], v[124:125], off offset:384
.LBB0_1012:
	ds_read_b128 v[192:195], v153 offset:32768
	s_andn2_b64 vcc, exec, s[8:9]
	s_waitcnt lgkmcnt(0)
	v_mfma_f32_32x32x16_bf16 v[32:47], v[192:195], v[218:221], v[32:47]
	v_mfma_f32_32x32x16_bf16 v[48:63], v[192:195], v[226:229], v[48:63]
	ds_read_b128 v[192:195], v157 offset:32768
	v_mfma_f32_32x32x16_bf16 v[0:15], v[222:225], v[218:221], v[0:15]
	ds_read_b128 v[218:221], v159 offset:49152
	v_mfma_f32_32x32x16_bf16 v[16:31], v[222:225], v[226:229], v[16:31]
	ds_read_b128 v[222:225], v157 offset:36864
	ds_read_b128 v[226:229], v159 offset:53248
	s_waitcnt vmcnt(8)
	ds_write_b128 v135, v[64:67]
	ds_write_b128 v135, v[72:75] offset:16384
	ds_write_b128 v135, v[80:83] offset:4096
	s_waitcnt lgkmcnt(3)
	v_mfma_f32_32x32x16_bf16 v[32:47], v[192:195], v[218:221], v[32:47]
	v_mfma_f32_32x32x16_bf16 v[48:63], v[192:195], v[226:229], v[48:63]
	ds_read_b128 v[192:195], v161 offset:32768
	v_mfma_f32_32x32x16_bf16 v[0:15], v[222:225], v[218:221], v[0:15]
	ds_read_b128 v[218:221], v163 offset:49152
	v_mfma_f32_32x32x16_bf16 v[16:31], v[222:225], v[226:229], v[16:31]
	ds_read_b128 v[222:225], v161 offset:36864
	ds_read_b128 v[226:229], v163 offset:53248
	ds_write_b128 v135, v[88:91] offset:20480
	ds_write_b128 v135, v[96:99] offset:8192
	ds_write_b128 v135, v[104:107] offset:24576
	s_waitcnt lgkmcnt(3)
	v_mfma_f32_32x32x16_bf16 v[32:47], v[192:195], v[218:221], v[32:47]
	v_mfma_f32_32x32x16_bf16 v[48:63], v[192:195], v[226:229], v[48:63]
	ds_read_b128 v[192:195], v165 offset:32768
	v_mfma_f32_32x32x16_bf16 v[0:15], v[222:225], v[218:221], v[0:15]
	ds_read_b128 v[218:221], v167 offset:49152
	v_mfma_f32_32x32x16_bf16 v[16:31], v[222:225], v[226:229], v[16:31]
	ds_read_b128 v[222:225], v165 offset:36864
	ds_read_b128 v[226:229], v167 offset:53248
	ds_write_b128 v135, v[112:115] offset:12288
	ds_write_b128 v135, v[120:123] offset:28672
	s_waitcnt lgkmcnt(2)
	v_mfma_f32_32x32x16_bf16 v[32:47], v[192:195], v[218:221], v[32:47]
	v_mfma_f32_32x32x16_bf16 v[48:63], v[192:195], v[226:229], v[48:63]
	v_mfma_f32_32x32x16_bf16 v[0:15], v[222:225], v[218:221], v[0:15]
	v_mfma_f32_32x32x16_bf16 v[16:31], v[222:225], v[226:229], v[16:31]
	s_branch .LBB0_1007

.LBB0_1508:
	v_add_u32_e32 v147, v142, v140
	s_waitcnt lgkmcnt(0)
	v_mfma_f32_32x32x16_bf16 v[16:31], v[156:159], v[152:155], v[16:31]
	s_cmp_gt_u32 s16, 12
	v_mfma_f32_32x32x16_bf16 v[48:63], v[148:151], v[152:155], v[48:63]
	v_mfma_f32_32x32x16_bf16 v[32:47], v[148:151], v[160:163], v[32:47]
	ds_read_b128 v[150:153], v147
	v_add_u32_e32 v148, v142, v141
	v_add_u32_e32 v149, v143, v140
	v_mfma_f32_32x32x16_bf16 v[0:15], v[156:159], v[160:163], v[0:15]
	ds_read_b128 v[154:157], v148 offset:16384
	ds_read_b128 v[158:161], v147 offset:4096
	ds_read_b128 v[162:165], v148 offset:20480
	s_mov_b64 vcc, s[4:5]
	s_cbranch_vccnz .Lg2w_w0
	s_waitcnt vmcnt(8)
	s_branch .Lg2w_w1

.Lg2w_w1:
	ds_write_b128 v138, v[68:71] offset:32768
	ds_write_b128 v138, v[76:79] offset:49152
	ds_write_b128 v138, v[84:87] offset:36864
	s_waitcnt lgkmcnt(3)
	v_mfma_f32_32x32x16_bf16 v[48:63], v[150:153], v[154:157], v[48:63]
	v_mfma_f32_32x32x16_bf16 v[32:47], v[150:153], v[162:165], v[32:47]
	v_add_u32_e32 v150, v143, v141
	v_add_u32_e32 v151, v144, v140
	v_mfma_f32_32x32x16_bf16 v[16:31], v[158:161], v[154:157], v[16:31]
	ds_read_b128 v[152:155], v149
	v_mfma_f32_32x32x16_bf16 v[0:15], v[158:161], v[162:165], v[0:15]
	ds_read_b128 v[156:159], v150 offset:16384
	ds_read_b128 v[160:163], v149 offset:4096
	ds_read_b128 v[170:173], v150 offset:20480
	ds_write_b128 v138, v[92:95] offset:53248
	ds_write_b128 v138, v[100:103] offset:40960
	ds_write_b128 v138, v[108:111] offset:57344
	s_waitcnt lgkmcnt(3)
	v_mfma_f32_32x32x16_bf16 v[48:63], v[152:155], v[156:159], v[48:63]
	v_mfma_f32_32x32x16_bf16 v[32:47], v[152:155], v[170:173], v[32:47]
	v_add_u32_e32 v152, v144, v141
	v_mfma_f32_32x32x16_bf16 v[16:31], v[160:163], v[156:159], v[16:31]
	ds_read_b128 v[154:157], v151
	v_mfma_f32_32x32x16_bf16 v[0:15], v[160:163], v[170:173], v[0:15]
	ds_read_b128 v[158:161], v152 offset:16384
	ds_read_b128 v[162:165], v151 offset:4096
	ds_read_b128 v[170:173], v152 offset:20480
	ds_write_b128 v138, v[116:119] offset:45056
	ds_write_b128 v138, v[124:127] offset:61440
	s_waitcnt lgkmcnt(2)
	v_mfma_f32_32x32x16_bf16 v[48:63], v[154:157], v[158:161], v[48:63]
	v_mfma_f32_32x32x16_bf16 v[32:47], v[154:157], v[170:173], v[32:47]
	v_mfma_f32_32x32x16_bf16 v[16:31], v[162:165], v[158:161], v[16:31]
	v_mfma_f32_32x32x16_bf16 v[0:15], v[162:165], v[170:173], v[0:15]
	s_waitcnt lgkmcnt(0)
	s_barrier
	ds_read_b128 v[154:157], v146 offset:49152
	ds_read_b128 v[158:161], v145 offset:36864
	ds_read_b128 v[162:165], v146 offset:53248
	s_cbranch_scc1 .LBB0_1510
	v_add_co_u32_e32 v84, vcc, 0x10000, v136
	global_load_dwordx4 v[68:71], v[136:137], off offset:384
	global_load_dwordx4 v[76:79], v[134:135], off offset:384
	v_addc_co_u32_e32 v85, vcc, 0, v137, vcc
	v_add_co_u32_e32 v92, vcc, 0x10000, v134
	global_load_dwordx4 v[84:87], v[84:85], off offset:384
	s_nop 0
	v_addc_co_u32_e32 v93, vcc, 0, v135, vcc
	v_add_co_u32_e32 v100, vcc, 0x20000, v136
	global_load_dwordx4 v[92:95], v[92:93], off offset:384
	s_nop 0
	v_addc_co_u32_e32 v101, vcc, 0, v137, vcc
	v_add_co_u32_e32 v108, vcc, 0x20000, v134
	global_load_dwordx4 v[100:103], v[100:101], off offset:384
	s_nop 0
	v_addc_co_u32_e32 v109, vcc, 0, v135, vcc
	v_add_co_u32_e32 v116, vcc, 0x30000, v136
	global_load_dwordx4 v[108:111], v[108:109], off offset:384
	s_nop 0
	v_addc_co_u32_e32 v117, vcc, 0, v137, vcc
	v_add_co_u32_e32 v124, vcc, 0x30000, v134
	global_load_dwordx4 v[116:119], v[116:117], off offset:384
	s_nop 0
	v_addc_co_u32_e32 v125, vcc, 0, v135, vcc
	global_load_dwordx4 v[124:127], v[124:125], off offset:384
.LBB0_1510:
	ds_read_b128 v[134:137], v145 offset:32768
	s_andn2_b64 vcc, exec, s[6:7]
	s_waitcnt lgkmcnt(0)
	v_mfma_f32_32x32x16_bf16 v[48:63], v[134:137], v[154:157], v[48:63]
	v_mfma_f32_32x32x16_bf16 v[32:47], v[134:137], v[162:165], v[32:47]
	ds_read_b128 v[134:137], v147 offset:32768
	v_mfma_f32_32x32x16_bf16 v[16:31], v[158:161], v[154:157], v[16:31]
	ds_read_b128 v[154:157], v148 offset:49152
	v_mfma_f32_32x32x16_bf16 v[0:15], v[158:161], v[162:165], v[0:15]
	ds_read_b128 v[158:161], v147 offset:36864
	ds_read_b128 v[162:165], v148 offset:53248
	s_waitcnt vmcnt(8)
	ds_write_b128 v138, v[64:67]
	ds_write_b128 v138, v[72:75] offset:16384
	ds_write_b128 v138, v[80:83] offset:4096
	s_waitcnt lgkmcnt(3)
	v_mfma_f32_32x32x16_bf16 v[48:63], v[134:137], v[154:157], v[48:63]
	v_mfma_f32_32x32x16_bf16 v[32:47], v[134:137], v[162:165], v[32:47]
	ds_read_b128 v[134:137], v149 offset:32768
	v_mfma_f32_32x32x16_bf16 v[16:31], v[158:161], v[154:157], v[16:31]
	ds_read_b128 v[154:157], v150 offset:49152
	ds_read_b128 v[146:149], v149 offset:36864
	v_mfma_f32_32x32x16_bf16 v[0:15], v[158:161], v[162:165], v[0:15]
	ds_read_b128 v[158:161], v150 offset:53248
	ds_write_b128 v138, v[88:91] offset:20480
	ds_write_b128 v138, v[96:99] offset:8192
	ds_write_b128 v138, v[104:107] offset:24576
	s_waitcnt lgkmcnt(3)
	v_mfma_f32_32x32x16_bf16 v[48:63], v[134:137], v[154:157], v[48:63]
	v_mfma_f32_32x32x16_bf16 v[32:47], v[134:137], v[158:161], v[32:47]
	ds_read_b128 v[134:137], v151 offset:32768
	v_mfma_f32_32x32x16_bf16 v[16:31], v[146:149], v[154:157], v[16:31]
	v_mfma_f32_32x32x16_bf16 v[0:15], v[146:149], v[158:161], v[0:15]
	ds_read_b128 v[146:149], v152 offset:49152
	ds_read_b128 v[154:157], v151 offset:36864
	ds_read_b128 v[150:153], v152 offset:53248
	ds_write_b128 v138, v[112:115] offset:12288
	ds_write_b128 v138, v[120:123] offset:28672
	s_waitcnt lgkmcnt(2)
	v_mfma_f32_32x32x16_bf16 v[48:63], v[134:137], v[146:149], v[48:63]
	v_mfma_f32_32x32x16_bf16 v[32:47], v[134:137], v[150:153], v[32:47]
	v_mfma_f32_32x32x16_bf16 v[16:31], v[154:157], v[146:149], v[16:31]
	v_mfma_f32_32x32x16_bf16 v[0:15], v[154:157], v[150:153], v[0:15]
	s_branch .LBB0_1505
